# GEMM matrix segments stripped to the 32 MFMAs only: no setprio flips or waits between the two barriers (prio set before the opening barrier, reset after the closing one)
# speedup vs baseline: 1.0179x; 1.0048x over previous
; #define PG8_STAGE(bufoff, gbase, voff) do { _Pragma("unroll") for (int _i = 0; _i < 2; ++_i) \
;         __builtin_amdgcn_global_load_lds((const unsigned*)((const char*)(gbase) + (voff)[_i]), (PG8_LAS unsigned*)(lds + (bufoff) + ldsw + _i * 8192), 16, 0, 0); } while (0)
; #define PG8_LDA(dst, b, h) do { _Pragma("unroll") for (int m = 0; m < 4; ++m) _Pragma("unroll") for (int k = 0; k < 2; ++k) dst[m][k] = *(const PG8_LAS bf16x8*)(lds + PG8_SA(b, h) + aoff + m * 2048 + k * 1024); } while (0)
; #define PG8_LDB(dst, b, h) do { _Pragma("unroll") for (int n = 0; n < 2; ++n) _Pragma("unroll") for (int k = 0; k < 2; ++k) dst[n][k] = *(const PG8_LAS bf16x8*)(lds + PG8_SB(b, h) + boff + n * 2048 + k * 1024); } while (0)
; #define PG8_MMA(ai, bj, At, Bt) do { __builtin_amdgcn_s_setprio(1); _Pragma("unroll") for (int m = 0; m < 4; ++m) _Pragma("unroll") for (int n = 0; n < 2; ++n) _Pragma("unroll") for (int k = 0; k < 2; ++k) \
;         acc[ai][bj][m][n] = __builtin_amdgcn_mfma_f32_16x16x32_bf16(Bt[n][k], At[m][k], acc[ai][bj][m][n], 0, 0, 0); __builtin_amdgcn_s_setprio(0); } while (0)
; #define PG8_WAIT_V(n) asm volatile("s_waitcnt vmcnt(" #n ")" ::: "memory")
; #define PG8_WAIT_L(n) asm volatile("s_waitcnt lgkmcnt(" #n ")" ::: "memory")
; #define PG8_BAR __builtin_amdgcn_s_barrier()
; #define PG8_SCHED __builtin_amdgcn_sched_barrier(0)
; template <class Epi, class Sched, bool ALIGN_EPI = false, bool SP2 = false>
; __device__ __forceinline__ void gemm_phase(PG8_LAS unsigned char* lds, const Gemm g, const Sched& S, const Epi& E) {
;     ...
;         for (int t = 0; t < nt; t += 2) {
;             const bool last = (t == nt - 2);
;             const char* a1 = cA + (size_t)(t + 1) * kstepB;
;             const char* a2 = last ? nA : cA + (size_t)(t + 2) * kstepB; const char* b2 = last ? nB : cB + (size_t)(t + 2) * kstepB;
;             const char* a3 = a2 + kstepB; const char* b3 = b2 + kstepB;
;             if (last && has_next) S.a_ready(nxt);
;             if constexpr (SP2) {
;             PG8_LDB(B0, 0, 0); PG8_LDB(B1, 0, 1); PG8_SCHED; PG8_LDA(At, 0, 0); PG8_STAGE(PG8_SA(1, 1), a1 + hstepB, voffA);
;             PG8_WAIT_V(8); PG8_WAIT_L(0); PG8_BAR; PG8_MMA(0, 0, At, B0); PG8_MMA(0, 1, At, B1); PG8_BAR; PG8_SCHED;
;             PG8_LDA(At, 0, 1); PG8_STAGE(PG8_SB(0, 0), b2, voffB); PG8_STAGE(PG8_SB(0, 1), b2 + hstepB, voffB); PG8_STAGE(PG8_SA(0, 0), a2, voffA);
.LBB0_193:
	s_add_i32 s84, s38, 2
	s_add_u32 s39, s36, 0x4000
	s_addc_u32 s40, s37, 0
	s_cmp_eq_u32 s31, s38
	s_cselect_b32 s42, s8, s39
	s_cselect_b32 s43, s9, s40
	s_cselect_b32 s40, s62, s78
	s_cselect_b32 s41, s63, s82
	s_add_u32 s38, s42, 0x8000
	s_addc_u32 s39, s43, 0
	s_add_i32 s90, 0, 0x10000
	s_add_i32 s64, 0, 0x14000
	v_add_u32_e32 v140, s90, v174
	v_add_u32_e32 v161, s64, v174
	ds_read_b128 v[128:131], v140
	ds_read_b128 v[132:135], v140 offset:1024
	ds_read_b128 v[136:139], v140 offset:2048
	ds_read_b128 v[140:143], v140 offset:3072
	ds_read_b128 v[144:147], v161
	ds_read_b128 v[148:151], v161 offset:1024
	ds_read_b128 v[178:181], v161 offset:2048
	ds_read_b128 v[182:185], v161 offset:3072
	v_lshl_add_u64 v[172:173], s[36:37], 0, v[168:169]
	s_add_i32 m0, s21, 0xc000
	ds_read_b128 v[186:189], v177
	ds_read_b128 v[190:193], v177 offset:1024
	ds_read_b128 v[194:197], v177 offset:2048
	ds_read_b128 v[198:201], v177 offset:3072
	ds_read_b128 v[202:205], v177 offset:4096
	ds_read_b128 v[206:209], v177 offset:5120
	ds_read_b128 v[210:213], v177 offset:6144
	ds_read_b128 v[214:217], v177 offset:7168
	global_load_lds_dwordx4 v[172:173], off
	v_lshl_add_u64 v[172:173], s[36:37], 0, v[170:171]
	s_add_i32 m0, s21, 0xe000
	s_nop 0
	global_load_lds_dwordx4 v[172:173], off
	s_setprio 1
	s_waitcnt vmcnt(8)
	s_waitcnt lgkmcnt(0)
	s_barrier
	v_mfma_f32_16x16x32_bf16 v[124:127], v[128:131], v[186:189], v[124:127]
	v_mfma_f32_16x16x32_bf16 v[124:127], v[132:135], v[190:193], v[124:127]
	v_mfma_f32_16x16x32_bf16 v[120:123], v[136:139], v[186:189], v[120:123]
	v_mfma_f32_16x16x32_bf16 v[120:123], v[140:143], v[190:193], v[120:123]
	v_mfma_f32_16x16x32_bf16 v[108:111], v[128:131], v[194:197], v[108:111]
	v_mfma_f32_16x16x32_bf16 v[108:111], v[132:135], v[198:201], v[108:111]
	v_mfma_f32_16x16x32_bf16 v[104:107], v[136:139], v[194:197], v[104:107]
	v_mfma_f32_16x16x32_bf16 v[104:107], v[140:143], v[198:201], v[104:107]
	v_mfma_f32_16x16x32_bf16 v[92:95], v[128:131], v[202:205], v[92:95]
	v_mfma_f32_16x16x32_bf16 v[92:95], v[132:135], v[206:209], v[92:95]
	v_mfma_f32_16x16x32_bf16 v[88:91], v[136:139], v[202:205], v[88:91]
	v_mfma_f32_16x16x32_bf16 v[88:91], v[140:143], v[206:209], v[88:91]
	v_mfma_f32_16x16x32_bf16 v[76:79], v[128:131], v[210:213], v[76:79]
	v_mfma_f32_16x16x32_bf16 v[76:79], v[132:135], v[214:217], v[76:79]
	v_mfma_f32_16x16x32_bf16 v[72:75], v[136:139], v[210:213], v[72:75]
	v_mfma_f32_16x16x32_bf16 v[72:75], v[140:143], v[214:217], v[72:75]
	v_mfma_f32_16x16x32_bf16 v[116:119], v[144:147], v[186:189], v[116:119]
	v_mfma_f32_16x16x32_bf16 v[116:119], v[148:151], v[190:193], v[116:119]
	v_mfma_f32_16x16x32_bf16 v[112:115], v[178:181], v[186:189], v[112:115]
	v_mfma_f32_16x16x32_bf16 v[112:115], v[182:185], v[190:193], v[112:115]
	v_mfma_f32_16x16x32_bf16 v[100:103], v[144:147], v[194:197], v[100:103]
	v_mfma_f32_16x16x32_bf16 v[100:103], v[148:151], v[198:201], v[100:103]
	v_mfma_f32_16x16x32_bf16 v[96:99], v[178:181], v[194:197], v[96:99]
	v_mfma_f32_16x16x32_bf16 v[96:99], v[182:185], v[198:201], v[96:99]
	v_mfma_f32_16x16x32_bf16 v[84:87], v[144:147], v[202:205], v[84:87]
	v_mfma_f32_16x16x32_bf16 v[84:87], v[148:151], v[206:209], v[84:87]
	v_mfma_f32_16x16x32_bf16 v[80:83], v[178:181], v[202:205], v[80:83]
	v_mfma_f32_16x16x32_bf16 v[80:83], v[182:185], v[206:209], v[80:83]
	v_mfma_f32_16x16x32_bf16 v[68:71], v[144:147], v[210:213], v[68:71]
	v_mfma_f32_16x16x32_bf16 v[68:71], v[148:151], v[214:217], v[68:71]
	v_mfma_f32_16x16x32_bf16 v[64:67], v[178:181], v[210:213], v[64:67]
	v_mfma_f32_16x16x32_bf16 v[64:67], v[182:185], v[214:217], v[64:67]
	s_barrier
	s_setprio 0
	s_add_i32 s65, s90, s20
	v_lshl_add_u64 v[172:173], s[40:41], 0, v[156:157]
	s_mov_b32 m0, s65
	ds_read_b128 v[186:189], v177 offset:16384
	ds_read_b128 v[190:193], v177 offset:17408
	ds_read_b128 v[194:197], v177 offset:18432
	ds_read_b128 v[198:201], v177 offset:19456
	ds_read_b128 v[202:205], v177 offset:20480
	ds_read_b128 v[206:209], v177 offset:21504
	ds_read_b128 v[210:213], v177 offset:22528
	ds_read_b128 v[214:217], v177 offset:23552
	global_load_lds_dwordx4 v[172:173], off
	s_add_i32 m0, s65, 0x2000
	s_add_u32 vcc_lo, s40, 0x4000
	v_lshl_add_u64 v[172:173], s[40:41], 0, v[152:153]
	s_addc_u32 vcc_hi, s41, 0
	s_add_i32 s64, s64, s20
	global_load_lds_dwordx4 v[172:173], off
	v_lshl_add_u64 v[172:173], vcc, 0, v[156:157]
	s_mov_b32 m0, s64
	s_nop 0
	global_load_lds_dwordx4 v[172:173], off
	v_lshl_add_u64 v[172:173], vcc, 0, v[152:153]
	s_add_i32 m0, s64, 0x2000
	s_nop 0
	global_load_lds_dwordx4 v[172:173], off
	v_lshl_add_u64 v[172:173], s[42:43], 0, v[158:159]
	s_mov_b32 m0, s21
	s_nop 0
	global_load_lds_dwordx4 v[172:173], off
	v_lshl_add_u64 v[172:173], s[42:43], 0, v[154:155]
	s_mov_b32 m0, s22
	s_nop 0
	global_load_lds_dwordx4 v[172:173], off
	s_setprio 1
	s_waitcnt vmcnt(8)
	s_waitcnt lgkmcnt(0)
	s_barrier
; #define PG8_STAGE(bufoff, gbase, voff) do { _Pragma("unroll") for (int _i = 0; _i < 2; ++_i) \
;         __builtin_amdgcn_global_load_lds((const unsigned*)((const char*)(gbase) + (voff)[_i]), (PG8_LAS unsigned*)(lds + (bufoff) + ldsw + _i * 8192), 16, 0, 0); } while (0)
; #define PG8_LDA(dst, b, h) do { _Pragma("unroll") for (int m = 0; m < 4; ++m) _Pragma("unroll") for (int k = 0; k < 2; ++k) dst[m][k] = *(const PG8_LAS bf16x8*)(lds + PG8_SA(b, h) + aoff + m * 2048 + k * 1024); } while (0)
; #define PG8_LDB(dst, b, h) do { _Pragma("unroll") for (int n = 0; n < 2; ++n) _Pragma("unroll") for (int k = 0; k < 2; ++k) dst[n][k] = *(const PG8_LAS bf16x8*)(lds + PG8_SB(b, h) + boff + n * 2048 + k * 1024); } while (0)
; #define PG8_MMA(ai, bj, At, Bt) do { __builtin_amdgcn_s_setprio(1); _Pragma("unroll") for (int m = 0; m < 4; ++m) _Pragma("unroll") for (int n = 0; n < 2; ++n) _Pragma("unroll") for (int k = 0; k < 2; ++k) \
;         acc[ai][bj][m][n] = __builtin_amdgcn_mfma_f32_16x16x32_bf16(Bt[n][k], At[m][k], acc[ai][bj][m][n], 0, 0, 0); __builtin_amdgcn_s_setprio(0); } while (0)
; #define PG8_WAIT_V(n) asm volatile("s_waitcnt vmcnt(" #n ")" ::: "memory")
; #define PG8_WAIT_L(n) asm volatile("s_waitcnt lgkmcnt(" #n ")" ::: "memory")
; #define PG8_BAR __builtin_amdgcn_s_barrier()
; #define PG8_SCHED __builtin_amdgcn_sched_barrier(0)
; template <class Epi, class Sched, bool ALIGN_EPI = false, bool SP2 = false>
; __device__ __forceinline__ void gemm_phase(PG8_LAS unsigned char* lds, const Gemm g, const Sched& S, const Epi& E) {
;     ...
;             PG8_WAIT_V(8); PG8_WAIT_L(0); PG8_BAR; PG8_MMA(1, 0, At, B0); PG8_MMA(1, 1, At, B1); PG8_BAR; PG8_SCHED;
;             PG8_LDB(B0, 1, 0); PG8_LDB(B1, 1, 1); PG8_SCHED; PG8_LDA(At, 1, 0); PG8_STAGE(PG8_SA(0, 1), a2 + hstepB, voffA);
;             PG8_WAIT_V(8); PG8_WAIT_L(0); PG8_BAR; PG8_MMA(0, 0, At, B0); PG8_MMA(0, 1, At, B1); PG8_BAR; PG8_SCHED;
	v_mfma_f32_16x16x32_bf16 v[60:63], v[128:131], v[186:189], v[60:63]
	v_mfma_f32_16x16x32_bf16 v[60:63], v[132:135], v[190:193], v[60:63]
	v_mfma_f32_16x16x32_bf16 v[56:59], v[136:139], v[186:189], v[56:59]
	v_mfma_f32_16x16x32_bf16 v[56:59], v[140:143], v[190:193], v[56:59]
	v_mfma_f32_16x16x32_bf16 v[44:47], v[128:131], v[194:197], v[44:47]
	v_mfma_f32_16x16x32_bf16 v[44:47], v[132:135], v[198:201], v[44:47]
	v_mfma_f32_16x16x32_bf16 v[40:43], v[136:139], v[194:197], v[40:43]
	v_mfma_f32_16x16x32_bf16 v[40:43], v[140:143], v[198:201], v[40:43]
	v_mfma_f32_16x16x32_bf16 v[28:31], v[128:131], v[202:205], v[28:31]
	v_mfma_f32_16x16x32_bf16 v[28:31], v[132:135], v[206:209], v[28:31]
	v_mfma_f32_16x16x32_bf16 v[24:27], v[136:139], v[202:205], v[24:27]
	v_mfma_f32_16x16x32_bf16 v[24:27], v[140:143], v[206:209], v[24:27]
	v_mfma_f32_16x16x32_bf16 v[12:15], v[128:131], v[210:213], v[12:15]
	v_mfma_f32_16x16x32_bf16 v[12:15], v[132:135], v[214:217], v[12:15]
	v_mfma_f32_16x16x32_bf16 v[8:11], v[136:139], v[210:213], v[8:11]
	v_mfma_f32_16x16x32_bf16 v[8:11], v[140:143], v[214:217], v[8:11]
	v_mfma_f32_16x16x32_bf16 v[52:55], v[144:147], v[186:189], v[52:55]
	v_mfma_f32_16x16x32_bf16 v[52:55], v[148:151], v[190:193], v[52:55]
	v_mfma_f32_16x16x32_bf16 v[48:51], v[178:181], v[186:189], v[48:51]
	v_mfma_f32_16x16x32_bf16 v[48:51], v[182:185], v[190:193], v[48:51]
	v_mfma_f32_16x16x32_bf16 v[36:39], v[144:147], v[194:197], v[36:39]
	v_mfma_f32_16x16x32_bf16 v[36:39], v[148:151], v[198:201], v[36:39]
	v_mfma_f32_16x16x32_bf16 v[32:35], v[178:181], v[194:197], v[32:35]
	v_mfma_f32_16x16x32_bf16 v[32:35], v[182:185], v[198:201], v[32:35]
	v_mfma_f32_16x16x32_bf16 v[20:23], v[144:147], v[202:205], v[20:23]
	v_mfma_f32_16x16x32_bf16 v[20:23], v[148:151], v[206:209], v[20:23]
	v_mfma_f32_16x16x32_bf16 v[16:19], v[178:181], v[202:205], v[16:19]
	v_mfma_f32_16x16x32_bf16 v[16:19], v[182:185], v[206:209], v[16:19]
	v_mfma_f32_16x16x32_bf16 v[4:7], v[144:147], v[210:213], v[4:7]
	v_mfma_f32_16x16x32_bf16 v[4:7], v[148:151], v[214:217], v[4:7]
	v_mfma_f32_16x16x32_bf16 v[0:3], v[178:181], v[210:213], v[0:3]
	v_mfma_f32_16x16x32_bf16 v[0:3], v[182:185], v[214:217], v[0:3]
	s_barrier
	s_setprio 0
	s_add_i32 s64, 0, 0x18000
	s_add_i32 s65, 0, 0x1c000
	v_add_u32_e32 v140, s64, v174
	v_add_u32_e32 v161, s65, v174
	ds_read_b128 v[128:131], v140
	ds_read_b128 v[132:135], v140 offset:1024
	ds_read_b128 v[136:139], v140 offset:2048
	ds_read_b128 v[140:143], v140 offset:3072
	ds_read_b128 v[144:147], v161
	ds_read_b128 v[148:151], v161 offset:1024
	ds_read_b128 v[178:181], v161 offset:2048
	ds_read_b128 v[182:185], v161 offset:3072
	s_add_u32 s42, s42, 0x4000
	s_addc_u32 s43, s43, 0
	s_mov_b32 m0, s23
	v_lshl_add_u64 v[172:173], s[42:43], 0, v[158:159]
	ds_read_b128 v[186:189], v177 offset:32768
	ds_read_b128 v[190:193], v177 offset:33792
	ds_read_b128 v[194:197], v177 offset:34816
	ds_read_b128 v[198:201], v177 offset:35840
	ds_read_b128 v[202:205], v177 offset:36864
	ds_read_b128 v[206:209], v177 offset:37888
	ds_read_b128 v[210:213], v177 offset:38912
	ds_read_b128 v[214:217], v177 offset:39936
	global_load_lds_dwordx4 v[172:173], off
	v_lshl_add_u64 v[172:173], s[42:43], 0, v[154:155]
	s_mov_b32 m0, s24
	s_nop 0
	global_load_lds_dwordx4 v[172:173], off
	s_setprio 1
	s_waitcnt vmcnt(8)
	s_waitcnt lgkmcnt(0)
	s_barrier
	v_mfma_f32_16x16x32_bf16 v[124:127], v[128:131], v[186:189], v[124:127]
	v_mfma_f32_16x16x32_bf16 v[124:127], v[132:135], v[190:193], v[124:127]
	v_mfma_f32_16x16x32_bf16 v[120:123], v[136:139], v[186:189], v[120:123]
	v_mfma_f32_16x16x32_bf16 v[120:123], v[140:143], v[190:193], v[120:123]
	v_mfma_f32_16x16x32_bf16 v[108:111], v[128:131], v[194:197], v[108:111]
	v_mfma_f32_16x16x32_bf16 v[108:111], v[132:135], v[198:201], v[108:111]
	v_mfma_f32_16x16x32_bf16 v[104:107], v[136:139], v[194:197], v[104:107]
	v_mfma_f32_16x16x32_bf16 v[104:107], v[140:143], v[198:201], v[104:107]
	v_mfma_f32_16x16x32_bf16 v[92:95], v[128:131], v[202:205], v[92:95]
	v_mfma_f32_16x16x32_bf16 v[92:95], v[132:135], v[206:209], v[92:95]
	v_mfma_f32_16x16x32_bf16 v[88:91], v[136:139], v[202:205], v[88:91]
	v_mfma_f32_16x16x32_bf16 v[88:91], v[140:143], v[206:209], v[88:91]
	v_mfma_f32_16x16x32_bf16 v[76:79], v[128:131], v[210:213], v[76:79]
	v_mfma_f32_16x16x32_bf16 v[76:79], v[132:135], v[214:217], v[76:79]
	v_mfma_f32_16x16x32_bf16 v[72:75], v[136:139], v[210:213], v[72:75]
	v_mfma_f32_16x16x32_bf16 v[72:75], v[140:143], v[214:217], v[72:75]
	v_mfma_f32_16x16x32_bf16 v[116:119], v[144:147], v[186:189], v[116:119]
	v_mfma_f32_16x16x32_bf16 v[116:119], v[148:151], v[190:193], v[116:119]
	v_mfma_f32_16x16x32_bf16 v[112:115], v[178:181], v[186:189], v[112:115]
	v_mfma_f32_16x16x32_bf16 v[112:115], v[182:185], v[190:193], v[112:115]
	v_mfma_f32_16x16x32_bf16 v[100:103], v[144:147], v[194:197], v[100:103]
	v_mfma_f32_16x16x32_bf16 v[100:103], v[148:151], v[198:201], v[100:103]
	v_mfma_f32_16x16x32_bf16 v[96:99], v[178:181], v[194:197], v[96:99]
	v_mfma_f32_16x16x32_bf16 v[96:99], v[182:185], v[198:201], v[96:99]
	v_mfma_f32_16x16x32_bf16 v[84:87], v[144:147], v[202:205], v[84:87]
	v_mfma_f32_16x16x32_bf16 v[84:87], v[148:151], v[206:209], v[84:87]
	v_mfma_f32_16x16x32_bf16 v[80:83], v[178:181], v[202:205], v[80:83]
	v_mfma_f32_16x16x32_bf16 v[80:83], v[182:185], v[206:209], v[80:83]
	v_mfma_f32_16x16x32_bf16 v[68:71], v[144:147], v[210:213], v[68:71]
	v_mfma_f32_16x16x32_bf16 v[68:71], v[148:151], v[214:217], v[68:71]
	v_mfma_f32_16x16x32_bf16 v[64:67], v[178:181], v[210:213], v[64:67]
	v_mfma_f32_16x16x32_bf16 v[64:67], v[182:185], v[214:217], v[64:67]
	s_barrier
; #define PG8_STAGE(bufoff, gbase, voff) do { _Pragma("unroll") for (int _i = 0; _i < 2; ++_i) \
;         __builtin_amdgcn_global_load_lds((const unsigned*)((const char*)(gbase) + (voff)[_i]), (PG8_LAS unsigned*)(lds + (bufoff) + ldsw + _i * 8192), 16, 0, 0); } while (0)
; #define PG8_LDA(dst, b, h) do { _Pragma("unroll") for (int m = 0; m < 4; ++m) _Pragma("unroll") for (int k = 0; k < 2; ++k) dst[m][k] = *(const PG8_LAS bf16x8*)(lds + PG8_SA(b, h) + aoff + m * 2048 + k * 1024); } while (0)
; #define PG8_MMA(ai, bj, At, Bt) do { __builtin_amdgcn_s_setprio(1); _Pragma("unroll") for (int m = 0; m < 4; ++m) _Pragma("unroll") for (int n = 0; n < 2; ++n) _Pragma("unroll") for (int k = 0; k < 2; ++k) \
;         acc[ai][bj][m][n] = __builtin_amdgcn_mfma_f32_16x16x32_bf16(Bt[n][k], At[m][k], acc[ai][bj][m][n], 0, 0, 0); __builtin_amdgcn_s_setprio(0); } while (0)
; #define PG8_WAIT_V(n) asm volatile("s_waitcnt vmcnt(" #n ")" ::: "memory")
; #define PG8_WAIT_L(n) asm volatile("s_waitcnt lgkmcnt(" #n ")" ::: "memory")
; #define PG8_BAR __builtin_amdgcn_s_barrier()
; #define PG8_SCHED __builtin_amdgcn_sched_barrier(0)
; template <class Epi, class Sched, bool ALIGN_EPI = false, bool SP2 = false>
; __device__ __forceinline__ void gemm_phase(PG8_LAS unsigned char* lds, const Gemm g, const Sched& S, const Epi& E) {
;     ...
;             PG8_LDA(At, 1, 1); PG8_STAGE(PG8_SB(1, 0), b3, voffB); PG8_STAGE(PG8_SB(1, 1), b3 + hstepB, voffB); PG8_STAGE(PG8_SA(1, 0), a3, voffA);
;             PG8_WAIT_V(8); PG8_WAIT_L(0); PG8_BAR; PG8_MMA(1, 0, At, B0); PG8_MMA(1, 1, At, B1); PG8_BAR; PG8_SCHED;
;     ...
;         if constexpr (ALIGN_EPI) { if (wr == 0) PG8_BAR; }
	s_setprio 0
	s_add_u32 s42, s40, 0x8000
	s_addc_u32 s43, s41, 0
	s_add_i32 s64, s64, s20
	v_lshl_add_u64 v[172:173], s[42:43], 0, v[156:157]
	s_mov_b32 m0, s64
	ds_read_b128 v[186:189], v177 offset:49152
	ds_read_b128 v[190:193], v177 offset:50176
	ds_read_b128 v[194:197], v177 offset:51200
	ds_read_b128 v[198:201], v177 offset:52224
	ds_read_b128 v[202:205], v177 offset:53248
	ds_read_b128 v[206:209], v177 offset:54272
	ds_read_b128 v[210:213], v177 offset:55296
	ds_read_b128 v[214:217], v177 offset:56320
	global_load_lds_dwordx4 v[172:173], off
	s_add_i32 m0, s64, 0x2000
	s_add_u32 s40, s40, 0xc000
	v_lshl_add_u64 v[172:173], s[42:43], 0, v[152:153]
	s_addc_u32 s41, s41, 0
	s_add_i32 s42, s65, s20
	global_load_lds_dwordx4 v[172:173], off
	v_lshl_add_u64 v[172:173], s[40:41], 0, v[156:157]
	s_mov_b32 m0, s42
	s_nop 0
	global_load_lds_dwordx4 v[172:173], off
	v_lshl_add_u64 v[172:173], s[40:41], 0, v[152:153]
	s_add_i32 m0, s42, 0x2000
	s_nop 0
	global_load_lds_dwordx4 v[172:173], off
	v_lshl_add_u64 v[172:173], s[38:39], 0, v[158:159]
	s_mov_b32 m0, s29
	s_nop 0
	global_load_lds_dwordx4 v[172:173], off
	v_lshl_add_u64 v[172:173], s[38:39], 0, v[154:155]
	s_mov_b32 m0, s30
	s_nop 0
	global_load_lds_dwordx4 v[172:173], off
	s_setprio 1
	s_waitcnt vmcnt(8)
	s_waitcnt lgkmcnt(0)
	s_barrier
	v_mfma_f32_16x16x32_bf16 v[60:63], v[128:131], v[186:189], v[60:63]
	v_mfma_f32_16x16x32_bf16 v[60:63], v[132:135], v[190:193], v[60:63]
	v_mfma_f32_16x16x32_bf16 v[56:59], v[136:139], v[186:189], v[56:59]
	v_mfma_f32_16x16x32_bf16 v[56:59], v[140:143], v[190:193], v[56:59]
	v_mfma_f32_16x16x32_bf16 v[44:47], v[128:131], v[194:197], v[44:47]
	v_mfma_f32_16x16x32_bf16 v[44:47], v[132:135], v[198:201], v[44:47]
	v_mfma_f32_16x16x32_bf16 v[40:43], v[136:139], v[194:197], v[40:43]
	v_mfma_f32_16x16x32_bf16 v[40:43], v[140:143], v[198:201], v[40:43]
	v_mfma_f32_16x16x32_bf16 v[28:31], v[128:131], v[202:205], v[28:31]
	v_mfma_f32_16x16x32_bf16 v[28:31], v[132:135], v[206:209], v[28:31]
	v_mfma_f32_16x16x32_bf16 v[24:27], v[136:139], v[202:205], v[24:27]
	v_mfma_f32_16x16x32_bf16 v[24:27], v[140:143], v[206:209], v[24:27]
	v_mfma_f32_16x16x32_bf16 v[12:15], v[128:131], v[210:213], v[12:15]
	v_mfma_f32_16x16x32_bf16 v[12:15], v[132:135], v[214:217], v[12:15]
	v_mfma_f32_16x16x32_bf16 v[8:11], v[136:139], v[210:213], v[8:11]
	v_mfma_f32_16x16x32_bf16 v[8:11], v[140:143], v[214:217], v[8:11]
	v_mfma_f32_16x16x32_bf16 v[52:55], v[144:147], v[186:189], v[52:55]
	v_mfma_f32_16x16x32_bf16 v[52:55], v[148:151], v[190:193], v[52:55]
	v_mfma_f32_16x16x32_bf16 v[48:51], v[178:181], v[186:189], v[48:51]
	v_mfma_f32_16x16x32_bf16 v[48:51], v[182:185], v[190:193], v[48:51]
	v_mfma_f32_16x16x32_bf16 v[36:39], v[144:147], v[194:197], v[36:39]
	v_mfma_f32_16x16x32_bf16 v[36:39], v[148:151], v[198:201], v[36:39]
	v_mfma_f32_16x16x32_bf16 v[32:35], v[178:181], v[194:197], v[32:35]
	v_mfma_f32_16x16x32_bf16 v[32:35], v[182:185], v[198:201], v[32:35]
	v_mfma_f32_16x16x32_bf16 v[20:23], v[144:147], v[202:205], v[20:23]
	v_mfma_f32_16x16x32_bf16 v[20:23], v[148:151], v[206:209], v[20:23]
	v_mfma_f32_16x16x32_bf16 v[16:19], v[178:181], v[202:205], v[16:19]
	v_mfma_f32_16x16x32_bf16 v[16:19], v[182:185], v[206:209], v[16:19]
	v_mfma_f32_16x16x32_bf16 v[4:7], v[144:147], v[210:213], v[4:7]
	v_mfma_f32_16x16x32_bf16 v[4:7], v[148:151], v[214:217], v[4:7]
	v_mfma_f32_16x16x32_bf16 v[0:3], v[178:181], v[210:213], v[0:3]
	v_mfma_f32_16x16x32_bf16 v[0:3], v[182:185], v[214:217], v[0:3]
	s_barrier
	s_setprio 0
	s_add_u32 s36, s36, 0x10000
	s_addc_u32 s37, s37, 0
	s_add_u32 s78, s78, 0x10000
	s_addc_u32 s82, s82, 0
	s_cmp_ge_u32 s84, s26
	s_mov_b32 s38, s84
	s_cbranch_scc0 .LBB0_193
	s_and_b64 vcc, exec, s[60:61]
	s_cbranch_vccz .LBB0_196
	s_barrier

; #define PG8_STAGE(bufoff, gbase, voff) do { _Pragma("unroll") for (int _i = 0; _i < 2; ++_i) \
;         __builtin_amdgcn_global_load_lds((const unsigned*)((const char*)(gbase) + (voff)[_i]), (PG8_LAS unsigned*)(lds + (bufoff) + ldsw + _i * 8192), 16, 0, 0); } while (0)
; #define PG8_LDA(dst, b, h) do { _Pragma("unroll") for (int m = 0; m < 4; ++m) _Pragma("unroll") for (int k = 0; k < 2; ++k) dst[m][k] = *(const PG8_LAS bf16x8*)(lds + PG8_SA(b, h) + aoff + m * 2048 + k * 1024); } while (0)
; #define PG8_LDB(dst, b, h) do { _Pragma("unroll") for (int n = 0; n < 2; ++n) _Pragma("unroll") for (int k = 0; k < 2; ++k) dst[n][k] = *(const PG8_LAS bf16x8*)(lds + PG8_SB(b, h) + boff + n * 2048 + k * 1024); } while (0)
; #define PG8_MMA(ai, bj, At, Bt) do { __builtin_amdgcn_s_setprio(1); _Pragma("unroll") for (int m = 0; m < 4; ++m) _Pragma("unroll") for (int n = 0; n < 2; ++n) _Pragma("unroll") for (int k = 0; k < 2; ++k) \
;         acc[ai][bj][m][n] = __builtin_amdgcn_mfma_f32_16x16x32_bf16(Bt[n][k], At[m][k], acc[ai][bj][m][n], 0, 0, 0); __builtin_amdgcn_s_setprio(0); } while (0)
; #define PG8_WAIT_V(n) asm volatile("s_waitcnt vmcnt(" #n ")" ::: "memory")
; #define PG8_WAIT_L(n) asm volatile("s_waitcnt lgkmcnt(" #n ")" ::: "memory")
; #define PG8_BAR __builtin_amdgcn_s_barrier()
; #define PG8_SCHED __builtin_amdgcn_sched_barrier(0)
; template <class Epi, class Sched, bool ALIGN_EPI = false, bool SP2 = false>
; __device__ __forceinline__ void gemm_phase(PG8_LAS unsigned char* lds, const Gemm g, const Sched& S, const Epi& E) {
;     ...
;         for (int t = 0; t < nt; t += 2) {
;             const bool last = (t == nt - 2);
;             const char* a1 = cA + (size_t)(t + 1) * kstepB;
;             const char* a2 = last ? nA : cA + (size_t)(t + 2) * kstepB; const char* b2 = last ? nB : cB + (size_t)(t + 2) * kstepB;
;             const char* a3 = a2 + kstepB; const char* b3 = b2 + kstepB;
;             if (last && has_next) S.a_ready(nxt);
;             if constexpr (SP2) {
;             PG8_LDB(B0, 0, 0); PG8_LDB(B1, 0, 1); PG8_SCHED; PG8_LDA(At, 0, 0); PG8_STAGE(PG8_SA(1, 1), a1 + hstepB, voffA);
;             PG8_WAIT_V(8); PG8_WAIT_L(0); PG8_BAR; PG8_MMA(0, 0, At, B0); PG8_MMA(0, 1, At, B1); PG8_BAR; PG8_SCHED;
;             PG8_LDA(At, 0, 1); PG8_STAGE(PG8_SB(0, 0), b2, voffB); PG8_STAGE(PG8_SB(0, 1), b2 + hstepB, voffB); PG8_STAGE(PG8_SA(0, 0), a2, voffA);
.LBB0_232:
	s_add_u32 s31, s36, 0x4000
	s_addc_u32 s38, s37, 0
	s_cmp_eq_u32 s30, 28
	s_cselect_b32 s42, s26, s31
	s_cselect_b32 s43, s13, s38
	s_cselect_b32 s40, s27, s28
	s_cselect_b32 s41, s11, s29
	s_add_u32 s38, s42, 0x8000
	s_addc_u32 s39, s43, 0
	s_add_i32 s31, 0, 0x10000
	s_add_i32 s60, 0, 0x14000
	v_add_u32_e32 v152, s31, v169
	v_add_u32_e32 v175, s60, v169
	ds_read_b128 v[128:131], v152
	ds_read_b128 v[132:135], v152 offset:1024
	ds_read_b128 v[148:151], v152 offset:2048
	ds_read_b128 v[152:155], v152 offset:3072
	ds_read_b128 v[156:159], v175
	ds_read_b128 v[160:163], v175 offset:1024
	ds_read_b128 v[164:167], v175 offset:2048
	ds_read_b128 v[176:179], v175 offset:3072
	v_lshl_add_u64 v[212:213], s[36:37], 0, v[144:145]
	s_add_i32 m0, s17, 0xc000
	ds_read_b128 v[180:183], v174
	ds_read_b128 v[184:187], v174 offset:1024
	ds_read_b128 v[188:191], v174 offset:2048
	ds_read_b128 v[192:195], v174 offset:3072
	ds_read_b128 v[196:199], v174 offset:4096
	ds_read_b128 v[200:203], v174 offset:5120
	ds_read_b128 v[204:207], v174 offset:6144
	ds_read_b128 v[208:211], v174 offset:7168
	global_load_lds_dwordx4 v[212:213], off
	v_lshl_add_u64 v[212:213], s[36:37], 0, v[146:147]
	s_add_i32 m0, s17, 0xe000
	s_nop 0
	global_load_lds_dwordx4 v[212:213], off
	s_setprio 1
	s_waitcnt vmcnt(8)
	s_waitcnt lgkmcnt(0)
	s_barrier
	v_mfma_f32_16x16x32_bf16 v[124:127], v[128:131], v[180:183], v[124:127]
	v_mfma_f32_16x16x32_bf16 v[124:127], v[132:135], v[184:187], v[124:127]
	v_mfma_f32_16x16x32_bf16 v[120:123], v[148:151], v[180:183], v[120:123]
	v_mfma_f32_16x16x32_bf16 v[120:123], v[152:155], v[184:187], v[120:123]
	v_mfma_f32_16x16x32_bf16 v[108:111], v[128:131], v[188:191], v[108:111]
	v_mfma_f32_16x16x32_bf16 v[108:111], v[132:135], v[192:195], v[108:111]
	v_mfma_f32_16x16x32_bf16 v[104:107], v[148:151], v[188:191], v[104:107]
	v_mfma_f32_16x16x32_bf16 v[104:107], v[152:155], v[192:195], v[104:107]
	v_mfma_f32_16x16x32_bf16 v[92:95], v[128:131], v[196:199], v[92:95]
	v_mfma_f32_16x16x32_bf16 v[92:95], v[132:135], v[200:203], v[92:95]
	v_mfma_f32_16x16x32_bf16 v[88:91], v[148:151], v[196:199], v[88:91]
	v_mfma_f32_16x16x32_bf16 v[88:91], v[152:155], v[200:203], v[88:91]
	v_mfma_f32_16x16x32_bf16 v[76:79], v[128:131], v[204:207], v[76:79]
	v_mfma_f32_16x16x32_bf16 v[76:79], v[132:135], v[208:211], v[76:79]
	v_mfma_f32_16x16x32_bf16 v[72:75], v[148:151], v[204:207], v[72:75]
	v_mfma_f32_16x16x32_bf16 v[72:75], v[152:155], v[208:211], v[72:75]
	v_mfma_f32_16x16x32_bf16 v[116:119], v[156:159], v[180:183], v[116:119]
	v_mfma_f32_16x16x32_bf16 v[116:119], v[160:163], v[184:187], v[116:119]
	v_mfma_f32_16x16x32_bf16 v[112:115], v[164:167], v[180:183], v[112:115]
	v_mfma_f32_16x16x32_bf16 v[112:115], v[176:179], v[184:187], v[112:115]
	v_mfma_f32_16x16x32_bf16 v[100:103], v[156:159], v[188:191], v[100:103]
	v_mfma_f32_16x16x32_bf16 v[100:103], v[160:163], v[192:195], v[100:103]
	v_mfma_f32_16x16x32_bf16 v[96:99], v[164:167], v[188:191], v[96:99]
	v_mfma_f32_16x16x32_bf16 v[96:99], v[176:179], v[192:195], v[96:99]
	v_mfma_f32_16x16x32_bf16 v[84:87], v[156:159], v[196:199], v[84:87]
	v_mfma_f32_16x16x32_bf16 v[84:87], v[160:163], v[200:203], v[84:87]
	v_mfma_f32_16x16x32_bf16 v[80:83], v[164:167], v[196:199], v[80:83]
	v_mfma_f32_16x16x32_bf16 v[80:83], v[176:179], v[200:203], v[80:83]
	v_mfma_f32_16x16x32_bf16 v[68:71], v[156:159], v[204:207], v[68:71]
	v_mfma_f32_16x16x32_bf16 v[68:71], v[160:163], v[208:211], v[68:71]
	v_mfma_f32_16x16x32_bf16 v[64:67], v[164:167], v[204:207], v[64:67]
	v_mfma_f32_16x16x32_bf16 v[64:67], v[176:179], v[208:211], v[64:67]
	s_barrier
	s_setprio 0
	s_add_i32 s31, s31, s14
	v_lshl_add_u64 v[212:213], s[40:41], 0, v[220:221]
	s_mov_b32 m0, s31
	ds_read_b128 v[180:183], v174 offset:16384
	ds_read_b128 v[184:187], v174 offset:17408
	ds_read_b128 v[188:191], v174 offset:18432
	ds_read_b128 v[192:195], v174 offset:19456
	ds_read_b128 v[196:199], v174 offset:20480
	ds_read_b128 v[200:203], v174 offset:21504
	ds_read_b128 v[204:207], v174 offset:22528
	ds_read_b128 v[208:211], v174 offset:23552
	global_load_lds_dwordx4 v[212:213], off
	s_add_i32 m0, s31, 0x2000
	s_add_u32 s44, s40, 0x4000
	v_lshl_add_u64 v[212:213], s[40:41], 0, v[136:137]
	s_addc_u32 s45, s41, 0
	s_add_i32 s31, s60, s14
	global_load_lds_dwordx4 v[212:213], off
	v_lshl_add_u64 v[212:213], s[44:45], 0, v[220:221]
	s_mov_b32 m0, s31
	s_nop 0
	global_load_lds_dwordx4 v[212:213], off
	v_lshl_add_u64 v[212:213], s[44:45], 0, v[136:137]
	s_add_i32 m0, s31, 0x2000
	s_nop 0
	global_load_lds_dwordx4 v[212:213], off
	v_lshl_add_u64 v[212:213], s[42:43], 0, v[140:141]
	s_mov_b32 m0, s17
	s_nop 0
	global_load_lds_dwordx4 v[212:213], off
	v_lshl_add_u64 v[212:213], s[42:43], 0, v[138:139]
	s_mov_b32 m0, s18
	s_nop 0
	global_load_lds_dwordx4 v[212:213], off
	s_setprio 1
	s_waitcnt vmcnt(8)
	s_waitcnt lgkmcnt(0)
	s_barrier
; #define PG8_STAGE(bufoff, gbase, voff) do { _Pragma("unroll") for (int _i = 0; _i < 2; ++_i) \
;         __builtin_amdgcn_global_load_lds((const unsigned*)((const char*)(gbase) + (voff)[_i]), (PG8_LAS unsigned*)(lds + (bufoff) + ldsw + _i * 8192), 16, 0, 0); } while (0)
; #define PG8_LDA(dst, b, h) do { _Pragma("unroll") for (int m = 0; m < 4; ++m) _Pragma("unroll") for (int k = 0; k < 2; ++k) dst[m][k] = *(const PG8_LAS bf16x8*)(lds + PG8_SA(b, h) + aoff + m * 2048 + k * 1024); } while (0)
; #define PG8_LDB(dst, b, h) do { _Pragma("unroll") for (int n = 0; n < 2; ++n) _Pragma("unroll") for (int k = 0; k < 2; ++k) dst[n][k] = *(const PG8_LAS bf16x8*)(lds + PG8_SB(b, h) + boff + n * 2048 + k * 1024); } while (0)
; #define PG8_MMA(ai, bj, At, Bt) do { __builtin_amdgcn_s_setprio(1); _Pragma("unroll") for (int m = 0; m < 4; ++m) _Pragma("unroll") for (int n = 0; n < 2; ++n) _Pragma("unroll") for (int k = 0; k < 2; ++k) \
;         acc[ai][bj][m][n] = __builtin_amdgcn_mfma_f32_16x16x32_bf16(Bt[n][k], At[m][k], acc[ai][bj][m][n], 0, 0, 0); __builtin_amdgcn_s_setprio(0); } while (0)
; #define PG8_WAIT_V(n) asm volatile("s_waitcnt vmcnt(" #n ")" ::: "memory")
; #define PG8_WAIT_L(n) asm volatile("s_waitcnt lgkmcnt(" #n ")" ::: "memory")
; #define PG8_BAR __builtin_amdgcn_s_barrier()
; #define PG8_SCHED __builtin_amdgcn_sched_barrier(0)
; template <class Epi, class Sched, bool ALIGN_EPI = false, bool SP2 = false>
; __device__ __forceinline__ void gemm_phase(PG8_LAS unsigned char* lds, const Gemm g, const Sched& S, const Epi& E) {
;     ...
;             PG8_WAIT_V(8); PG8_WAIT_L(0); PG8_BAR; PG8_MMA(1, 0, At, B0); PG8_MMA(1, 1, At, B1); PG8_BAR; PG8_SCHED;
;             PG8_LDB(B0, 1, 0); PG8_LDB(B1, 1, 1); PG8_SCHED; PG8_LDA(At, 1, 0); PG8_STAGE(PG8_SA(0, 1), a2 + hstepB, voffA);
;             PG8_WAIT_V(8); PG8_WAIT_L(0); PG8_BAR; PG8_MMA(0, 0, At, B0); PG8_MMA(0, 1, At, B1); PG8_BAR; PG8_SCHED;
	v_mfma_f32_16x16x32_bf16 v[60:63], v[128:131], v[180:183], v[60:63]
	v_mfma_f32_16x16x32_bf16 v[60:63], v[132:135], v[184:187], v[60:63]
	v_mfma_f32_16x16x32_bf16 v[56:59], v[148:151], v[180:183], v[56:59]
	v_mfma_f32_16x16x32_bf16 v[56:59], v[152:155], v[184:187], v[56:59]
	v_mfma_f32_16x16x32_bf16 v[48:51], v[128:131], v[188:191], v[48:51]
	v_mfma_f32_16x16x32_bf16 v[48:51], v[132:135], v[192:195], v[48:51]
	v_mfma_f32_16x16x32_bf16 v[40:43], v[148:151], v[188:191], v[40:43]
	v_mfma_f32_16x16x32_bf16 v[40:43], v[152:155], v[192:195], v[40:43]
	v_mfma_f32_16x16x32_bf16 v[32:35], v[128:131], v[196:199], v[32:35]
	v_mfma_f32_16x16x32_bf16 v[32:35], v[132:135], v[200:203], v[32:35]
	v_mfma_f32_16x16x32_bf16 v[24:27], v[148:151], v[196:199], v[24:27]
	v_mfma_f32_16x16x32_bf16 v[24:27], v[152:155], v[200:203], v[24:27]
	v_mfma_f32_16x16x32_bf16 v[16:19], v[128:131], v[204:207], v[16:19]
	v_mfma_f32_16x16x32_bf16 v[16:19], v[132:135], v[208:211], v[16:19]
	v_mfma_f32_16x16x32_bf16 v[8:11], v[148:151], v[204:207], v[8:11]
	v_mfma_f32_16x16x32_bf16 v[8:11], v[152:155], v[208:211], v[8:11]
	v_mfma_f32_16x16x32_bf16 v[52:55], v[156:159], v[180:183], v[52:55]
	v_mfma_f32_16x16x32_bf16 v[52:55], v[160:163], v[184:187], v[52:55]
	v_mfma_f32_16x16x32_bf16 v[44:47], v[164:167], v[180:183], v[44:47]
	v_mfma_f32_16x16x32_bf16 v[44:47], v[176:179], v[184:187], v[44:47]
	v_mfma_f32_16x16x32_bf16 v[36:39], v[156:159], v[188:191], v[36:39]
	v_mfma_f32_16x16x32_bf16 v[36:39], v[160:163], v[192:195], v[36:39]
	v_mfma_f32_16x16x32_bf16 v[28:31], v[164:167], v[188:191], v[28:31]
	v_mfma_f32_16x16x32_bf16 v[28:31], v[176:179], v[192:195], v[28:31]
	v_mfma_f32_16x16x32_bf16 v[20:23], v[156:159], v[196:199], v[20:23]
	v_mfma_f32_16x16x32_bf16 v[20:23], v[160:163], v[200:203], v[20:23]
	v_mfma_f32_16x16x32_bf16 v[12:15], v[164:167], v[196:199], v[12:15]
	v_mfma_f32_16x16x32_bf16 v[12:15], v[176:179], v[200:203], v[12:15]
	v_mfma_f32_16x16x32_bf16 v[4:7], v[156:159], v[204:207], v[4:7]
	v_mfma_f32_16x16x32_bf16 v[4:7], v[160:163], v[208:211], v[4:7]
	v_mfma_f32_16x16x32_bf16 v[0:3], v[164:167], v[204:207], v[0:3]
	v_mfma_f32_16x16x32_bf16 v[0:3], v[176:179], v[208:211], v[0:3]
	s_barrier
	s_setprio 0
	s_add_i32 s31, 0, 0x18000
	s_add_i32 s44, 0, 0x1c000
	v_add_u32_e32 v152, s31, v169
	v_add_u32_e32 v175, s44, v169
	ds_read_b128 v[128:131], v152
	ds_read_b128 v[132:135], v152 offset:1024
	ds_read_b128 v[148:151], v152 offset:2048
	ds_read_b128 v[152:155], v152 offset:3072
	ds_read_b128 v[156:159], v175
	ds_read_b128 v[160:163], v175 offset:1024
	ds_read_b128 v[164:167], v175 offset:2048
	ds_read_b128 v[176:179], v175 offset:3072
	s_add_u32 s42, s42, 0x4000
	s_addc_u32 s43, s43, 0
	s_mov_b32 m0, s19
	v_lshl_add_u64 v[212:213], s[42:43], 0, v[140:141]
	ds_read_b128 v[180:183], v174 offset:32768
	ds_read_b128 v[184:187], v174 offset:33792
	ds_read_b128 v[188:191], v174 offset:34816
	ds_read_b128 v[192:195], v174 offset:35840
	ds_read_b128 v[196:199], v174 offset:36864
	ds_read_b128 v[200:203], v174 offset:37888
	ds_read_b128 v[204:207], v174 offset:38912
	ds_read_b128 v[208:211], v174 offset:39936
	global_load_lds_dwordx4 v[212:213], off
	v_lshl_add_u64 v[212:213], s[42:43], 0, v[138:139]
	s_mov_b32 m0, s20
	s_nop 0
	global_load_lds_dwordx4 v[212:213], off
	s_setprio 1
	s_waitcnt vmcnt(8)
	s_waitcnt lgkmcnt(0)
	s_barrier
	v_mfma_f32_16x16x32_bf16 v[124:127], v[128:131], v[180:183], v[124:127]
	v_mfma_f32_16x16x32_bf16 v[124:127], v[132:135], v[184:187], v[124:127]
	v_mfma_f32_16x16x32_bf16 v[120:123], v[148:151], v[180:183], v[120:123]
	v_mfma_f32_16x16x32_bf16 v[120:123], v[152:155], v[184:187], v[120:123]
	v_mfma_f32_16x16x32_bf16 v[108:111], v[128:131], v[188:191], v[108:111]
	v_mfma_f32_16x16x32_bf16 v[108:111], v[132:135], v[192:195], v[108:111]
	v_mfma_f32_16x16x32_bf16 v[104:107], v[148:151], v[188:191], v[104:107]
	v_mfma_f32_16x16x32_bf16 v[104:107], v[152:155], v[192:195], v[104:107]
	v_mfma_f32_16x16x32_bf16 v[92:95], v[128:131], v[196:199], v[92:95]
	v_mfma_f32_16x16x32_bf16 v[92:95], v[132:135], v[200:203], v[92:95]
	v_mfma_f32_16x16x32_bf16 v[88:91], v[148:151], v[196:199], v[88:91]
	v_mfma_f32_16x16x32_bf16 v[88:91], v[152:155], v[200:203], v[88:91]
	v_mfma_f32_16x16x32_bf16 v[76:79], v[128:131], v[204:207], v[76:79]
	v_mfma_f32_16x16x32_bf16 v[76:79], v[132:135], v[208:211], v[76:79]
	v_mfma_f32_16x16x32_bf16 v[72:75], v[148:151], v[204:207], v[72:75]
	v_mfma_f32_16x16x32_bf16 v[72:75], v[152:155], v[208:211], v[72:75]
	v_mfma_f32_16x16x32_bf16 v[116:119], v[156:159], v[180:183], v[116:119]
	v_mfma_f32_16x16x32_bf16 v[116:119], v[160:163], v[184:187], v[116:119]
	v_mfma_f32_16x16x32_bf16 v[112:115], v[164:167], v[180:183], v[112:115]
	v_mfma_f32_16x16x32_bf16 v[112:115], v[176:179], v[184:187], v[112:115]
	v_mfma_f32_16x16x32_bf16 v[100:103], v[156:159], v[188:191], v[100:103]
	v_mfma_f32_16x16x32_bf16 v[100:103], v[160:163], v[192:195], v[100:103]
	v_mfma_f32_16x16x32_bf16 v[96:99], v[164:167], v[188:191], v[96:99]
	v_mfma_f32_16x16x32_bf16 v[96:99], v[176:179], v[192:195], v[96:99]
	v_mfma_f32_16x16x32_bf16 v[84:87], v[156:159], v[196:199], v[84:87]
	v_mfma_f32_16x16x32_bf16 v[84:87], v[160:163], v[200:203], v[84:87]
	v_mfma_f32_16x16x32_bf16 v[80:83], v[164:167], v[196:199], v[80:83]
	v_mfma_f32_16x16x32_bf16 v[80:83], v[176:179], v[200:203], v[80:83]
	v_mfma_f32_16x16x32_bf16 v[68:71], v[156:159], v[204:207], v[68:71]
	v_mfma_f32_16x16x32_bf16 v[68:71], v[160:163], v[208:211], v[68:71]
	v_mfma_f32_16x16x32_bf16 v[64:67], v[164:167], v[204:207], v[64:67]
	v_mfma_f32_16x16x32_bf16 v[64:67], v[176:179], v[208:211], v[64:67]
	s_barrier
; #define PG8_STAGE(bufoff, gbase, voff) do { _Pragma("unroll") for (int _i = 0; _i < 2; ++_i) \
;         __builtin_amdgcn_global_load_lds((const unsigned*)((const char*)(gbase) + (voff)[_i]), (PG8_LAS unsigned*)(lds + (bufoff) + ldsw + _i * 8192), 16, 0, 0); } while (0)
; #define PG8_LDA(dst, b, h) do { _Pragma("unroll") for (int m = 0; m < 4; ++m) _Pragma("unroll") for (int k = 0; k < 2; ++k) dst[m][k] = *(const PG8_LAS bf16x8*)(lds + PG8_SA(b, h) + aoff + m * 2048 + k * 1024); } while (0)
; #define PG8_MMA(ai, bj, At, Bt) do { __builtin_amdgcn_s_setprio(1); _Pragma("unroll") for (int m = 0; m < 4; ++m) _Pragma("unroll") for (int n = 0; n < 2; ++n) _Pragma("unroll") for (int k = 0; k < 2; ++k) \
;         acc[ai][bj][m][n] = __builtin_amdgcn_mfma_f32_16x16x32_bf16(Bt[n][k], At[m][k], acc[ai][bj][m][n], 0, 0, 0); __builtin_amdgcn_s_setprio(0); } while (0)
; #define PG8_WAIT_V(n) asm volatile("s_waitcnt vmcnt(" #n ")" ::: "memory")
; #define PG8_WAIT_L(n) asm volatile("s_waitcnt lgkmcnt(" #n ")" ::: "memory")
; #define PG8_BAR __builtin_amdgcn_s_barrier()
; #define PG8_SCHED __builtin_amdgcn_sched_barrier(0)
; template <class Epi, class Sched, bool ALIGN_EPI = false, bool SP2 = false>
; __device__ __forceinline__ void gemm_phase(PG8_LAS unsigned char* lds, const Gemm g, const Sched& S, const Epi& E) {
;     ...
;             PG8_LDA(At, 1, 1); PG8_STAGE(PG8_SB(1, 0), b3, voffB); PG8_STAGE(PG8_SB(1, 1), b3 + hstepB, voffB); PG8_STAGE(PG8_SA(1, 0), a3, voffA);
;             PG8_WAIT_V(8); PG8_WAIT_L(0); PG8_BAR; PG8_MMA(1, 0, At, B0); PG8_MMA(1, 1, At, B1); PG8_BAR; PG8_SCHED;
;     ...
;         if constexpr (ALIGN_EPI) { if (wr == 0) PG8_BAR; }
	s_setprio 0
	s_add_u32 s42, s40, 0x8000
	s_addc_u32 s43, s41, 0
	s_add_i32 s31, s31, s14
	v_lshl_add_u64 v[212:213], s[42:43], 0, v[220:221]
	s_mov_b32 m0, s31
	ds_read_b128 v[180:183], v174 offset:49152
	ds_read_b128 v[184:187], v174 offset:50176
	ds_read_b128 v[188:191], v174 offset:51200
	ds_read_b128 v[192:195], v174 offset:52224
	ds_read_b128 v[196:199], v174 offset:53248
	ds_read_b128 v[200:203], v174 offset:54272
	ds_read_b128 v[204:207], v174 offset:55296
	ds_read_b128 v[208:211], v174 offset:56320
	global_load_lds_dwordx4 v[212:213], off
	s_add_i32 m0, s31, 0x2000
	s_add_u32 s40, s40, 0xc000
	v_lshl_add_u64 v[212:213], s[42:43], 0, v[136:137]
	s_addc_u32 s41, s41, 0
	s_add_i32 s31, s44, s14
	global_load_lds_dwordx4 v[212:213], off
	v_lshl_add_u64 v[212:213], s[40:41], 0, v[220:221]
	s_mov_b32 m0, s31
	s_nop 0
	global_load_lds_dwordx4 v[212:213], off
	v_lshl_add_u64 v[212:213], s[40:41], 0, v[136:137]
	s_add_i32 m0, s31, 0x2000
	s_nop 0
	global_load_lds_dwordx4 v[212:213], off
	v_lshl_add_u64 v[212:213], s[38:39], 0, v[140:141]
	s_mov_b32 m0, s21
	s_nop 0
	global_load_lds_dwordx4 v[212:213], off
	v_lshl_add_u64 v[212:213], s[38:39], 0, v[138:139]
	s_mov_b32 m0, s22
	s_nop 0
	global_load_lds_dwordx4 v[212:213], off
	s_setprio 1
	s_waitcnt vmcnt(8)
	s_waitcnt lgkmcnt(0)
	s_barrier
	v_mfma_f32_16x16x32_bf16 v[60:63], v[128:131], v[180:183], v[60:63]
	v_mfma_f32_16x16x32_bf16 v[60:63], v[132:135], v[184:187], v[60:63]
	v_mfma_f32_16x16x32_bf16 v[56:59], v[148:151], v[180:183], v[56:59]
	v_mfma_f32_16x16x32_bf16 v[56:59], v[152:155], v[184:187], v[56:59]
	v_mfma_f32_16x16x32_bf16 v[48:51], v[128:131], v[188:191], v[48:51]
	v_mfma_f32_16x16x32_bf16 v[48:51], v[132:135], v[192:195], v[48:51]
	v_mfma_f32_16x16x32_bf16 v[40:43], v[148:151], v[188:191], v[40:43]
	v_mfma_f32_16x16x32_bf16 v[40:43], v[152:155], v[192:195], v[40:43]
	v_mfma_f32_16x16x32_bf16 v[32:35], v[128:131], v[196:199], v[32:35]
	v_mfma_f32_16x16x32_bf16 v[32:35], v[132:135], v[200:203], v[32:35]
	v_mfma_f32_16x16x32_bf16 v[24:27], v[148:151], v[196:199], v[24:27]
	v_mfma_f32_16x16x32_bf16 v[24:27], v[152:155], v[200:203], v[24:27]
	v_mfma_f32_16x16x32_bf16 v[16:19], v[128:131], v[204:207], v[16:19]
	v_mfma_f32_16x16x32_bf16 v[16:19], v[132:135], v[208:211], v[16:19]
	v_mfma_f32_16x16x32_bf16 v[8:11], v[148:151], v[204:207], v[8:11]
	v_mfma_f32_16x16x32_bf16 v[8:11], v[152:155], v[208:211], v[8:11]
	v_mfma_f32_16x16x32_bf16 v[52:55], v[156:159], v[180:183], v[52:55]
	v_mfma_f32_16x16x32_bf16 v[52:55], v[160:163], v[184:187], v[52:55]
	v_mfma_f32_16x16x32_bf16 v[44:47], v[164:167], v[180:183], v[44:47]
	v_mfma_f32_16x16x32_bf16 v[44:47], v[176:179], v[184:187], v[44:47]
	v_mfma_f32_16x16x32_bf16 v[36:39], v[156:159], v[188:191], v[36:39]
	v_mfma_f32_16x16x32_bf16 v[36:39], v[160:163], v[192:195], v[36:39]
	v_mfma_f32_16x16x32_bf16 v[28:31], v[164:167], v[188:191], v[28:31]
	v_mfma_f32_16x16x32_bf16 v[28:31], v[176:179], v[192:195], v[28:31]
	v_mfma_f32_16x16x32_bf16 v[20:23], v[156:159], v[196:199], v[20:23]
	v_mfma_f32_16x16x32_bf16 v[20:23], v[160:163], v[200:203], v[20:23]
	v_mfma_f32_16x16x32_bf16 v[12:15], v[164:167], v[196:199], v[12:15]
	v_mfma_f32_16x16x32_bf16 v[12:15], v[176:179], v[200:203], v[12:15]
	v_mfma_f32_16x16x32_bf16 v[4:7], v[156:159], v[204:207], v[4:7]
	v_mfma_f32_16x16x32_bf16 v[4:7], v[160:163], v[208:211], v[4:7]
	v_mfma_f32_16x16x32_bf16 v[0:3], v[164:167], v[204:207], v[0:3]
	v_mfma_f32_16x16x32_bf16 v[0:3], v[176:179], v[208:211], v[0:3]
	s_barrier
	s_setprio 0
	s_add_i32 s30, s30, 2
	s_add_u32 s36, s36, 0x10000
	s_addc_u32 s37, s37, 0
	s_add_u32 s28, s28, 0x10000
	s_addc_u32 s29, s29, 0
	s_cmp_gt_u32 s30, 29
	s_cbranch_scc0 .LBB0_232
	s_and_b64 vcc, exec, s[8:9]
	s_cbranch_vccz .LBB0_235
	s_barrier

; #define PG8_STAGE(bufoff, gbase, voff) do { _Pragma("unroll") for (int _i = 0; _i < 2; ++_i) \
;         __builtin_amdgcn_global_load_lds((const unsigned*)((const char*)(gbase) + (voff)[_i]), (PG8_LAS unsigned*)(lds + (bufoff) + ldsw + _i * 8192), 16, 0, 0); } while (0)
; #define PG8_LDA(dst, b, h) do { _Pragma("unroll") for (int m = 0; m < 4; ++m) _Pragma("unroll") for (int k = 0; k < 2; ++k) dst[m][k] = *(const PG8_LAS bf16x8*)(lds + PG8_SA(b, h) + aoff + m * 2048 + k * 1024); } while (0)
; #define PG8_LDB(dst, b, h) do { _Pragma("unroll") for (int n = 0; n < 2; ++n) _Pragma("unroll") for (int k = 0; k < 2; ++k) dst[n][k] = *(const PG8_LAS bf16x8*)(lds + PG8_SB(b, h) + boff + n * 2048 + k * 1024); } while (0)
; #define PG8_MMA(ai, bj, At, Bt) do { __builtin_amdgcn_s_setprio(1); _Pragma("unroll") for (int m = 0; m < 4; ++m) _Pragma("unroll") for (int n = 0; n < 2; ++n) _Pragma("unroll") for (int k = 0; k < 2; ++k) \
;         acc[ai][bj][m][n] = __builtin_amdgcn_mfma_f32_16x16x32_bf16(Bt[n][k], At[m][k], acc[ai][bj][m][n], 0, 0, 0); __builtin_amdgcn_s_setprio(0); } while (0)
; #define PG8_WAIT_V(n) asm volatile("s_waitcnt vmcnt(" #n ")" ::: "memory")
; #define PG8_WAIT_L(n) asm volatile("s_waitcnt lgkmcnt(" #n ")" ::: "memory")
; #define PG8_BAR __builtin_amdgcn_s_barrier()
; #define PG8_SCHED __builtin_amdgcn_sched_barrier(0)
; template <class Epi, class Sched, bool ALIGN_EPI = false, bool SP2 = false>
; __device__ __forceinline__ void gemm_phase(PG8_LAS unsigned char* lds, const Gemm g, const Sched& S, const Epi& E) {
;     ...
;         for (int t = 0; t < nt; t += 2) {
;             const bool last = (t == nt - 2);
;             const char* a1 = cA + (size_t)(t + 1) * kstepB;
;             const char* a2 = last ? nA : cA + (size_t)(t + 2) * kstepB; const char* b2 = last ? nB : cB + (size_t)(t + 2) * kstepB;
;             const char* a3 = a2 + kstepB; const char* b3 = b2 + kstepB;
;             if (last && has_next) S.a_ready(nxt);
;             if constexpr (SP2) {
;             PG8_LDB(B0, 0, 0); PG8_LDB(B1, 0, 1); PG8_SCHED; PG8_LDA(At, 0, 0); PG8_STAGE(PG8_SA(1, 1), a1 + hstepB, voffA);
;             PG8_WAIT_V(8); PG8_WAIT_L(0); PG8_BAR; PG8_MMA(0, 0, At, B0); PG8_MMA(0, 1, At, B1); PG8_BAR; PG8_SCHED;
;             PG8_LDA(At, 0, 1); PG8_STAGE(PG8_SB(0, 0), b2, voffB); PG8_STAGE(PG8_SB(0, 1), b2 + hstepB, voffB); PG8_STAGE(PG8_SA(0, 0), a2, voffA);
.LBB0_263:
	s_add_u32 s38, s36, 0x4000
	s_addc_u32 s39, s37, 0
	s_cmp_eq_u32 s62, 28
	s_cselect_b32 s42, s30, s38
	s_cselect_b32 s43, s13, s39
	s_cselect_b32 s40, s31, s44
	s_cselect_b32 s41, s11, s45
	s_add_u32 s38, s42, 0x8000
	s_addc_u32 s39, s43, 0
	s_add_i32 s63, 0, 0x10000
	v_add_u32_e32 v151, s63, v165
	s_add_i32 s75, 0, 0x14000
	ds_read_b128 v[128:131], v151
	ds_read_b128 v[132:135], v151 offset:1024
	ds_read_b128 v[152:155], v151 offset:2048
	ds_read_b128 v[156:159], v151 offset:3072
	v_add_u32_e32 v151, s75, v165
	ds_read_b128 v[160:163], v151
	ds_read_b128 v[170:173], v151 offset:1024
	ds_read_b128 v[174:177], v151 offset:2048
	ds_read_b128 v[178:181], v151 offset:3072
	v_lshl_add_u64 v[214:215], s[36:37], 0, v[146:147]
	s_add_i32 m0, s19, 0xc000
	ds_read_b128 v[182:185], v168
	ds_read_b128 v[186:189], v168 offset:1024
	ds_read_b128 v[190:193], v168 offset:2048
	ds_read_b128 v[194:197], v168 offset:3072
	ds_read_b128 v[198:201], v168 offset:4096
	ds_read_b128 v[202:205], v168 offset:5120
	ds_read_b128 v[206:209], v168 offset:6144
	ds_read_b128 v[210:213], v168 offset:7168
	global_load_lds_dwordx4 v[214:215], off
	v_lshl_add_u64 v[214:215], s[36:37], 0, v[148:149]
	s_add_i32 m0, s19, 0xe000
	s_nop 0
	global_load_lds_dwordx4 v[214:215], off
	s_setprio 1
	s_waitcnt vmcnt(8)
	s_waitcnt lgkmcnt(0)
	s_barrier
	v_mfma_f32_16x16x32_bf16 v[124:127], v[128:131], v[182:185], v[124:127]
	v_mfma_f32_16x16x32_bf16 v[124:127], v[132:135], v[186:189], v[124:127]
	v_mfma_f32_16x16x32_bf16 v[116:119], v[152:155], v[182:185], v[116:119]
	v_mfma_f32_16x16x32_bf16 v[116:119], v[156:159], v[186:189], v[116:119]
	v_mfma_f32_16x16x32_bf16 v[108:111], v[128:131], v[190:193], v[108:111]
	v_mfma_f32_16x16x32_bf16 v[108:111], v[132:135], v[194:197], v[108:111]
	v_mfma_f32_16x16x32_bf16 v[100:103], v[152:155], v[190:193], v[100:103]
	v_mfma_f32_16x16x32_bf16 v[100:103], v[156:159], v[194:197], v[100:103]
	v_mfma_f32_16x16x32_bf16 v[92:95], v[128:131], v[198:201], v[92:95]
	v_mfma_f32_16x16x32_bf16 v[92:95], v[132:135], v[202:205], v[92:95]
	v_mfma_f32_16x16x32_bf16 v[84:87], v[152:155], v[198:201], v[84:87]
	v_mfma_f32_16x16x32_bf16 v[84:87], v[156:159], v[202:205], v[84:87]
	v_mfma_f32_16x16x32_bf16 v[76:79], v[128:131], v[206:209], v[76:79]
	v_mfma_f32_16x16x32_bf16 v[76:79], v[132:135], v[210:213], v[76:79]
	v_mfma_f32_16x16x32_bf16 v[68:71], v[152:155], v[206:209], v[68:71]
	v_mfma_f32_16x16x32_bf16 v[68:71], v[156:159], v[210:213], v[68:71]
	v_mfma_f32_16x16x32_bf16 v[120:123], v[160:163], v[182:185], v[120:123]
	v_mfma_f32_16x16x32_bf16 v[120:123], v[170:173], v[186:189], v[120:123]
	v_mfma_f32_16x16x32_bf16 v[112:115], v[174:177], v[182:185], v[112:115]
	v_mfma_f32_16x16x32_bf16 v[112:115], v[178:181], v[186:189], v[112:115]
	v_mfma_f32_16x16x32_bf16 v[104:107], v[160:163], v[190:193], v[104:107]
	v_mfma_f32_16x16x32_bf16 v[104:107], v[170:173], v[194:197], v[104:107]
	v_mfma_f32_16x16x32_bf16 v[96:99], v[174:177], v[190:193], v[96:99]
	v_mfma_f32_16x16x32_bf16 v[96:99], v[178:181], v[194:197], v[96:99]
	v_mfma_f32_16x16x32_bf16 v[88:91], v[160:163], v[198:201], v[88:91]
	v_mfma_f32_16x16x32_bf16 v[88:91], v[170:173], v[202:205], v[88:91]
	v_mfma_f32_16x16x32_bf16 v[80:83], v[174:177], v[198:201], v[80:83]
	v_mfma_f32_16x16x32_bf16 v[80:83], v[178:181], v[202:205], v[80:83]
	v_mfma_f32_16x16x32_bf16 v[72:75], v[160:163], v[206:209], v[72:75]
	v_mfma_f32_16x16x32_bf16 v[72:75], v[170:173], v[210:213], v[72:75]
	v_mfma_f32_16x16x32_bf16 v[64:67], v[174:177], v[206:209], v[64:67]
	v_mfma_f32_16x16x32_bf16 v[64:67], v[178:181], v[210:213], v[64:67]
	s_barrier
	s_setprio 0
	s_add_i32 s63, s63, s16
	v_lshl_add_u64 v[214:215], s[40:41], 0, v[140:141]
	s_mov_b32 m0, s63
	ds_read_b128 v[182:185], v168 offset:16384
	ds_read_b128 v[186:189], v168 offset:17408
	ds_read_b128 v[190:193], v168 offset:18432
	ds_read_b128 v[194:197], v168 offset:19456
	ds_read_b128 v[198:201], v168 offset:20480
	ds_read_b128 v[202:205], v168 offset:21504
	ds_read_b128 v[206:209], v168 offset:22528
	ds_read_b128 v[210:213], v168 offset:23552
	global_load_lds_dwordx4 v[214:215], off
	s_add_i32 m0, s63, 0x2000
	s_add_u32 s66, s40, 0x4000
	v_lshl_add_u64 v[214:215], s[40:41], 0, v[136:137]
	s_addc_u32 s67, s41, 0
	s_add_i32 s63, s75, s16
	global_load_lds_dwordx4 v[214:215], off
	v_lshl_add_u64 v[214:215], s[66:67], 0, v[140:141]
	s_mov_b32 m0, s63
	s_nop 0
	global_load_lds_dwordx4 v[214:215], off
	v_lshl_add_u64 v[214:215], s[66:67], 0, v[136:137]
	s_add_i32 m0, s63, 0x2000
	s_nop 0
	global_load_lds_dwordx4 v[214:215], off
	v_lshl_add_u64 v[214:215], s[42:43], 0, v[142:143]
	s_mov_b32 m0, s19
	s_nop 0
	global_load_lds_dwordx4 v[214:215], off
	v_lshl_add_u64 v[214:215], s[42:43], 0, v[138:139]
	s_mov_b32 m0, s20
	s_nop 0
	global_load_lds_dwordx4 v[214:215], off
	s_setprio 1
	s_waitcnt vmcnt(8)
	s_waitcnt lgkmcnt(0)
	s_barrier
; #define PG8_STAGE(bufoff, gbase, voff) do { _Pragma("unroll") for (int _i = 0; _i < 2; ++_i) \
;         __builtin_amdgcn_global_load_lds((const unsigned*)((const char*)(gbase) + (voff)[_i]), (PG8_LAS unsigned*)(lds + (bufoff) + ldsw + _i * 8192), 16, 0, 0); } while (0)
; #define PG8_LDA(dst, b, h) do { _Pragma("unroll") for (int m = 0; m < 4; ++m) _Pragma("unroll") for (int k = 0; k < 2; ++k) dst[m][k] = *(const PG8_LAS bf16x8*)(lds + PG8_SA(b, h) + aoff + m * 2048 + k * 1024); } while (0)
; #define PG8_LDB(dst, b, h) do { _Pragma("unroll") for (int n = 0; n < 2; ++n) _Pragma("unroll") for (int k = 0; k < 2; ++k) dst[n][k] = *(const PG8_LAS bf16x8*)(lds + PG8_SB(b, h) + boff + n * 2048 + k * 1024); } while (0)
; #define PG8_MMA(ai, bj, At, Bt) do { __builtin_amdgcn_s_setprio(1); _Pragma("unroll") for (int m = 0; m < 4; ++m) _Pragma("unroll") for (int n = 0; n < 2; ++n) _Pragma("unroll") for (int k = 0; k < 2; ++k) \
;         acc[ai][bj][m][n] = __builtin_amdgcn_mfma_f32_16x16x32_bf16(Bt[n][k], At[m][k], acc[ai][bj][m][n], 0, 0, 0); __builtin_amdgcn_s_setprio(0); } while (0)
; #define PG8_WAIT_V(n) asm volatile("s_waitcnt vmcnt(" #n ")" ::: "memory")
; #define PG8_WAIT_L(n) asm volatile("s_waitcnt lgkmcnt(" #n ")" ::: "memory")
; #define PG8_BAR __builtin_amdgcn_s_barrier()
; #define PG8_SCHED __builtin_amdgcn_sched_barrier(0)
; template <class Epi, class Sched, bool ALIGN_EPI = false, bool SP2 = false>
; __device__ __forceinline__ void gemm_phase(PG8_LAS unsigned char* lds, const Gemm g, const Sched& S, const Epi& E) {
;     ...
;             PG8_WAIT_V(8); PG8_WAIT_L(0); PG8_BAR; PG8_MMA(1, 0, At, B0); PG8_MMA(1, 1, At, B1); PG8_BAR; PG8_SCHED;
;             PG8_LDB(B0, 1, 0); PG8_LDB(B1, 1, 1); PG8_SCHED; PG8_LDA(At, 1, 0); PG8_STAGE(PG8_SA(0, 1), a2 + hstepB, voffA);
;             PG8_WAIT_V(8); PG8_WAIT_L(0); PG8_BAR; PG8_MMA(0, 0, At, B0); PG8_MMA(0, 1, At, B1); PG8_BAR; PG8_SCHED;
	v_mfma_f32_16x16x32_bf16 v[60:63], v[128:131], v[182:185], v[60:63]
	v_mfma_f32_16x16x32_bf16 v[60:63], v[132:135], v[186:189], v[60:63]
	v_mfma_f32_16x16x32_bf16 v[52:55], v[152:155], v[182:185], v[52:55]
	v_mfma_f32_16x16x32_bf16 v[52:55], v[156:159], v[186:189], v[52:55]
	v_mfma_f32_16x16x32_bf16 v[44:47], v[128:131], v[190:193], v[44:47]
	v_mfma_f32_16x16x32_bf16 v[44:47], v[132:135], v[194:197], v[44:47]
	v_mfma_f32_16x16x32_bf16 v[36:39], v[152:155], v[190:193], v[36:39]
	v_mfma_f32_16x16x32_bf16 v[36:39], v[156:159], v[194:197], v[36:39]
	v_mfma_f32_16x16x32_bf16 v[28:31], v[128:131], v[198:201], v[28:31]
	v_mfma_f32_16x16x32_bf16 v[28:31], v[132:135], v[202:205], v[28:31]
	v_mfma_f32_16x16x32_bf16 v[20:23], v[152:155], v[198:201], v[20:23]
	v_mfma_f32_16x16x32_bf16 v[20:23], v[156:159], v[202:205], v[20:23]
	v_mfma_f32_16x16x32_bf16 v[12:15], v[128:131], v[206:209], v[12:15]
	v_mfma_f32_16x16x32_bf16 v[12:15], v[132:135], v[210:213], v[12:15]
	v_mfma_f32_16x16x32_bf16 v[4:7], v[152:155], v[206:209], v[4:7]
	v_mfma_f32_16x16x32_bf16 v[4:7], v[156:159], v[210:213], v[4:7]
	v_mfma_f32_16x16x32_bf16 v[56:59], v[160:163], v[182:185], v[56:59]
	v_mfma_f32_16x16x32_bf16 v[56:59], v[170:173], v[186:189], v[56:59]
	v_mfma_f32_16x16x32_bf16 v[48:51], v[174:177], v[182:185], v[48:51]
	v_mfma_f32_16x16x32_bf16 v[48:51], v[178:181], v[186:189], v[48:51]
	v_mfma_f32_16x16x32_bf16 v[40:43], v[160:163], v[190:193], v[40:43]
	v_mfma_f32_16x16x32_bf16 v[40:43], v[170:173], v[194:197], v[40:43]
	v_mfma_f32_16x16x32_bf16 v[32:35], v[174:177], v[190:193], v[32:35]
	v_mfma_f32_16x16x32_bf16 v[32:35], v[178:181], v[194:197], v[32:35]
	v_mfma_f32_16x16x32_bf16 v[24:27], v[160:163], v[198:201], v[24:27]
	v_mfma_f32_16x16x32_bf16 v[24:27], v[170:173], v[202:205], v[24:27]
	v_mfma_f32_16x16x32_bf16 v[16:19], v[174:177], v[198:201], v[16:19]
	v_mfma_f32_16x16x32_bf16 v[16:19], v[178:181], v[202:205], v[16:19]
	v_mfma_f32_16x16x32_bf16 v[8:11], v[160:163], v[206:209], v[8:11]
	v_mfma_f32_16x16x32_bf16 v[8:11], v[170:173], v[210:213], v[8:11]
	v_mfma_f32_16x16x32_bf16 v[0:3], v[174:177], v[206:209], v[0:3]
	v_mfma_f32_16x16x32_bf16 v[0:3], v[178:181], v[210:213], v[0:3]
	s_barrier
	s_setprio 0
	s_add_i32 s63, 0, 0x18000
	v_add_u32_e32 v151, s63, v165
	s_add_i32 s66, 0, 0x1c000
	ds_read_b128 v[128:131], v151
	ds_read_b128 v[132:135], v151 offset:1024
	ds_read_b128 v[152:155], v151 offset:2048
	ds_read_b128 v[156:159], v151 offset:3072
	v_add_u32_e32 v151, s66, v165
	ds_read_b128 v[160:163], v151
	ds_read_b128 v[170:173], v151 offset:1024
	ds_read_b128 v[174:177], v151 offset:2048
	ds_read_b128 v[178:181], v151 offset:3072
	s_add_u32 s42, s42, 0x4000
	s_addc_u32 s43, s43, 0
	s_mov_b32 m0, s21
	v_lshl_add_u64 v[214:215], s[42:43], 0, v[142:143]
	ds_read_b128 v[182:185], v168 offset:32768
	ds_read_b128 v[186:189], v168 offset:33792
	ds_read_b128 v[190:193], v168 offset:34816
	ds_read_b128 v[194:197], v168 offset:35840
	ds_read_b128 v[198:201], v168 offset:36864
	ds_read_b128 v[202:205], v168 offset:37888
	ds_read_b128 v[206:209], v168 offset:38912
	ds_read_b128 v[210:213], v168 offset:39936
	global_load_lds_dwordx4 v[214:215], off
	v_lshl_add_u64 v[214:215], s[42:43], 0, v[138:139]
	s_mov_b32 m0, s22
	s_nop 0
	global_load_lds_dwordx4 v[214:215], off
	s_setprio 1
	s_waitcnt vmcnt(8)
	s_waitcnt lgkmcnt(0)
	s_barrier
	v_mfma_f32_16x16x32_bf16 v[124:127], v[128:131], v[182:185], v[124:127]
	v_mfma_f32_16x16x32_bf16 v[124:127], v[132:135], v[186:189], v[124:127]
	v_mfma_f32_16x16x32_bf16 v[116:119], v[152:155], v[182:185], v[116:119]
	v_mfma_f32_16x16x32_bf16 v[116:119], v[156:159], v[186:189], v[116:119]
	v_mfma_f32_16x16x32_bf16 v[108:111], v[128:131], v[190:193], v[108:111]
	v_mfma_f32_16x16x32_bf16 v[108:111], v[132:135], v[194:197], v[108:111]
	v_mfma_f32_16x16x32_bf16 v[100:103], v[152:155], v[190:193], v[100:103]
	v_mfma_f32_16x16x32_bf16 v[100:103], v[156:159], v[194:197], v[100:103]
	v_mfma_f32_16x16x32_bf16 v[92:95], v[128:131], v[198:201], v[92:95]
	v_mfma_f32_16x16x32_bf16 v[92:95], v[132:135], v[202:205], v[92:95]
	v_mfma_f32_16x16x32_bf16 v[84:87], v[152:155], v[198:201], v[84:87]
	v_mfma_f32_16x16x32_bf16 v[84:87], v[156:159], v[202:205], v[84:87]
	v_mfma_f32_16x16x32_bf16 v[76:79], v[128:131], v[206:209], v[76:79]
	v_mfma_f32_16x16x32_bf16 v[76:79], v[132:135], v[210:213], v[76:79]
	v_mfma_f32_16x16x32_bf16 v[68:71], v[152:155], v[206:209], v[68:71]
	v_mfma_f32_16x16x32_bf16 v[68:71], v[156:159], v[210:213], v[68:71]
	v_mfma_f32_16x16x32_bf16 v[120:123], v[160:163], v[182:185], v[120:123]
	v_mfma_f32_16x16x32_bf16 v[120:123], v[170:173], v[186:189], v[120:123]
	v_mfma_f32_16x16x32_bf16 v[112:115], v[174:177], v[182:185], v[112:115]
	v_mfma_f32_16x16x32_bf16 v[112:115], v[178:181], v[186:189], v[112:115]
	v_mfma_f32_16x16x32_bf16 v[104:107], v[160:163], v[190:193], v[104:107]
	v_mfma_f32_16x16x32_bf16 v[104:107], v[170:173], v[194:197], v[104:107]
	v_mfma_f32_16x16x32_bf16 v[96:99], v[174:177], v[190:193], v[96:99]
	v_mfma_f32_16x16x32_bf16 v[96:99], v[178:181], v[194:197], v[96:99]
	v_mfma_f32_16x16x32_bf16 v[88:91], v[160:163], v[198:201], v[88:91]
	v_mfma_f32_16x16x32_bf16 v[88:91], v[170:173], v[202:205], v[88:91]
	v_mfma_f32_16x16x32_bf16 v[80:83], v[174:177], v[198:201], v[80:83]
	v_mfma_f32_16x16x32_bf16 v[80:83], v[178:181], v[202:205], v[80:83]
	v_mfma_f32_16x16x32_bf16 v[72:75], v[160:163], v[206:209], v[72:75]
	v_mfma_f32_16x16x32_bf16 v[72:75], v[170:173], v[210:213], v[72:75]
	v_mfma_f32_16x16x32_bf16 v[64:67], v[174:177], v[206:209], v[64:67]
	v_mfma_f32_16x16x32_bf16 v[64:67], v[178:181], v[210:213], v[64:67]
	s_barrier
; #define PG8_STAGE(bufoff, gbase, voff) do { _Pragma("unroll") for (int _i = 0; _i < 2; ++_i) \
;         __builtin_amdgcn_global_load_lds((const unsigned*)((const char*)(gbase) + (voff)[_i]), (PG8_LAS unsigned*)(lds + (bufoff) + ldsw + _i * 8192), 16, 0, 0); } while (0)
; #define PG8_LDA(dst, b, h) do { _Pragma("unroll") for (int m = 0; m < 4; ++m) _Pragma("unroll") for (int k = 0; k < 2; ++k) dst[m][k] = *(const PG8_LAS bf16x8*)(lds + PG8_SA(b, h) + aoff + m * 2048 + k * 1024); } while (0)
; #define PG8_MMA(ai, bj, At, Bt) do { __builtin_amdgcn_s_setprio(1); _Pragma("unroll") for (int m = 0; m < 4; ++m) _Pragma("unroll") for (int n = 0; n < 2; ++n) _Pragma("unroll") for (int k = 0; k < 2; ++k) \
;         acc[ai][bj][m][n] = __builtin_amdgcn_mfma_f32_16x16x32_bf16(Bt[n][k], At[m][k], acc[ai][bj][m][n], 0, 0, 0); __builtin_amdgcn_s_setprio(0); } while (0)
; #define PG8_WAIT_V(n) asm volatile("s_waitcnt vmcnt(" #n ")" ::: "memory")
; #define PG8_WAIT_L(n) asm volatile("s_waitcnt lgkmcnt(" #n ")" ::: "memory")
; #define PG8_BAR __builtin_amdgcn_s_barrier()
; #define PG8_SCHED __builtin_amdgcn_sched_barrier(0)
; template <class Epi, class Sched, bool ALIGN_EPI = false, bool SP2 = false>
; __device__ __forceinline__ void gemm_phase(PG8_LAS unsigned char* lds, const Gemm g, const Sched& S, const Epi& E) {
;     ...
;             PG8_LDA(At, 1, 1); PG8_STAGE(PG8_SB(1, 0), b3, voffB); PG8_STAGE(PG8_SB(1, 1), b3 + hstepB, voffB); PG8_STAGE(PG8_SA(1, 0), a3, voffA);
;             PG8_WAIT_V(8); PG8_WAIT_L(0); PG8_BAR; PG8_MMA(1, 0, At, B0); PG8_MMA(1, 1, At, B1); PG8_BAR; PG8_SCHED;
;     ...
;         if constexpr (ALIGN_EPI) { if (wr == 0) PG8_BAR; }
	s_setprio 0
	s_add_u32 s42, s40, 0x8000
	s_addc_u32 s43, s41, 0
	s_add_i32 s63, s63, s16
	v_lshl_add_u64 v[214:215], s[42:43], 0, v[140:141]
	s_mov_b32 m0, s63
	ds_read_b128 v[182:185], v168 offset:49152
	ds_read_b128 v[186:189], v168 offset:50176
	ds_read_b128 v[190:193], v168 offset:51200
	ds_read_b128 v[194:197], v168 offset:52224
	ds_read_b128 v[198:201], v168 offset:53248
	ds_read_b128 v[202:205], v168 offset:54272
	ds_read_b128 v[206:209], v168 offset:55296
	ds_read_b128 v[210:213], v168 offset:56320
	global_load_lds_dwordx4 v[214:215], off
	s_add_i32 m0, s63, 0x2000
	s_add_u32 s40, s40, 0xc000
	v_lshl_add_u64 v[214:215], s[42:43], 0, v[136:137]
	s_addc_u32 s41, s41, 0
	s_add_i32 s42, s66, s16
	global_load_lds_dwordx4 v[214:215], off
	v_lshl_add_u64 v[214:215], s[40:41], 0, v[140:141]
	s_mov_b32 m0, s42
	s_nop 0
	global_load_lds_dwordx4 v[214:215], off
	v_lshl_add_u64 v[214:215], s[40:41], 0, v[136:137]
	s_add_i32 m0, s42, 0x2000
	s_nop 0
	global_load_lds_dwordx4 v[214:215], off
	v_lshl_add_u64 v[214:215], s[38:39], 0, v[142:143]
	s_mov_b32 m0, s25
	s_nop 0
	global_load_lds_dwordx4 v[214:215], off
	v_lshl_add_u64 v[214:215], s[38:39], 0, v[138:139]
	s_mov_b32 m0, s26
	s_nop 0
	global_load_lds_dwordx4 v[214:215], off
	s_setprio 1
	s_waitcnt vmcnt(8)
	s_waitcnt lgkmcnt(0)
	s_barrier
	v_mfma_f32_16x16x32_bf16 v[60:63], v[128:131], v[182:185], v[60:63]
	v_mfma_f32_16x16x32_bf16 v[60:63], v[132:135], v[186:189], v[60:63]
	v_mfma_f32_16x16x32_bf16 v[52:55], v[152:155], v[182:185], v[52:55]
	v_mfma_f32_16x16x32_bf16 v[52:55], v[156:159], v[186:189], v[52:55]
	v_mfma_f32_16x16x32_bf16 v[44:47], v[128:131], v[190:193], v[44:47]
	v_mfma_f32_16x16x32_bf16 v[44:47], v[132:135], v[194:197], v[44:47]
	v_mfma_f32_16x16x32_bf16 v[36:39], v[152:155], v[190:193], v[36:39]
	v_mfma_f32_16x16x32_bf16 v[36:39], v[156:159], v[194:197], v[36:39]
	v_mfma_f32_16x16x32_bf16 v[28:31], v[128:131], v[198:201], v[28:31]
	v_mfma_f32_16x16x32_bf16 v[28:31], v[132:135], v[202:205], v[28:31]
	v_mfma_f32_16x16x32_bf16 v[20:23], v[152:155], v[198:201], v[20:23]
	v_mfma_f32_16x16x32_bf16 v[20:23], v[156:159], v[202:205], v[20:23]
	v_mfma_f32_16x16x32_bf16 v[12:15], v[128:131], v[206:209], v[12:15]
	v_mfma_f32_16x16x32_bf16 v[12:15], v[132:135], v[210:213], v[12:15]
	v_mfma_f32_16x16x32_bf16 v[4:7], v[152:155], v[206:209], v[4:7]
	v_mfma_f32_16x16x32_bf16 v[4:7], v[156:159], v[210:213], v[4:7]
	v_mfma_f32_16x16x32_bf16 v[56:59], v[160:163], v[182:185], v[56:59]
	v_mfma_f32_16x16x32_bf16 v[56:59], v[170:173], v[186:189], v[56:59]
	v_mfma_f32_16x16x32_bf16 v[48:51], v[174:177], v[182:185], v[48:51]
	v_mfma_f32_16x16x32_bf16 v[48:51], v[178:181], v[186:189], v[48:51]
	v_mfma_f32_16x16x32_bf16 v[40:43], v[160:163], v[190:193], v[40:43]
	v_mfma_f32_16x16x32_bf16 v[40:43], v[170:173], v[194:197], v[40:43]
	v_mfma_f32_16x16x32_bf16 v[32:35], v[174:177], v[190:193], v[32:35]
	v_mfma_f32_16x16x32_bf16 v[32:35], v[178:181], v[194:197], v[32:35]
	v_mfma_f32_16x16x32_bf16 v[24:27], v[160:163], v[198:201], v[24:27]
	v_mfma_f32_16x16x32_bf16 v[24:27], v[170:173], v[202:205], v[24:27]
	v_mfma_f32_16x16x32_bf16 v[16:19], v[174:177], v[198:201], v[16:19]
	v_mfma_f32_16x16x32_bf16 v[16:19], v[178:181], v[202:205], v[16:19]
	v_mfma_f32_16x16x32_bf16 v[8:11], v[160:163], v[206:209], v[8:11]
	v_mfma_f32_16x16x32_bf16 v[8:11], v[170:173], v[210:213], v[8:11]
	v_mfma_f32_16x16x32_bf16 v[0:3], v[174:177], v[206:209], v[0:3]
	v_mfma_f32_16x16x32_bf16 v[0:3], v[178:181], v[210:213], v[0:3]
	s_barrier
	s_setprio 0
	s_add_i32 s62, s62, 2
	s_add_u32 s36, s36, 0x10000
	s_addc_u32 s37, s37, 0
	s_add_u32 s44, s44, 0x10000
	s_addc_u32 s45, s45, 0
	s_cmp_gt_u32 s62, 29
	s_cbranch_scc0 .LBB0_263
	s_and_b64 vcc, exec, s[8:9]
	s_cbranch_vccz .LBB0_266
	s_barrier
